# attention steps: removed quieting self-max around the row-max permlane and the +0 add at the end of the row-sum chain
# baseline (speedup 1.0000x reference)
.LBB0_148:
	v_add_u32_e32 v168, s6, v221
	ds_read_b64_tr_b16 v[164:165], v168 offset:24576
	ds_read_b64_tr_b16 v[166:167], v168 offset:25088
	v_mfma_f32_32x32x16_bf16 v[64:79], v[156:159], v[116:119], v[64:79]
	v_add_f32_e32 v104, v80, v81
	v_add_f32_e32 v104, v82, v104
	v_add_f32_e32 v104, v83, v104
	v_add_f32_e32 v104, v84, v104
	v_add_f32_e32 v104, v85, v104
	v_cvt_pk_bf16_f32 v124, v80, v81
	v_cvt_pk_bf16_f32 v125, v82, v83
	ds_read_b64_tr_b16 v[160:161], v168 offset:28672
	ds_read_b64_tr_b16 v[162:163], v168 offset:29184
	v_mfma_f32_32x32x16_bf16 v[48:63], v[152:155], v[116:119], v[48:63]
	v_add_f32_e32 v80, v86, v104
	v_add_f32_e32 v80, v87, v80
	v_add_f32_e32 v80, v88, v80
	v_add_f32_e32 v80, v89, v80
	v_cvt_pk_bf16_f32 v126, v84, v85
	v_cvt_pk_bf16_f32 v127, v86, v87
	ds_read_b64_tr_b16 v[152:153], v168 offset:25600
	ds_read_b64_tr_b16 v[154:155], v168 offset:26112
	v_mfma_f32_32x32x16_bf16 v[64:79], v[148:151], v[108:111], v[64:79]
	v_add_f32_e32 v80, v90, v80
	v_add_f32_e32 v80, v91, v80
	v_add_f32_e32 v80, v92, v80
	v_add_f32_e32 v80, v93, v80
	v_cvt_pk_bf16_f32 v120, v88, v89
	v_cvt_pk_bf16_f32 v121, v90, v91
	ds_read_b64_tr_b16 v[148:149], v168 offset:29696
	ds_read_b64_tr_b16 v[150:151], v168 offset:30208
	v_mfma_f32_32x32x16_bf16 v[48:63], v[144:147], v[108:111], v[48:63]
	v_add_f32_e32 v80, v94, v80
	v_add_f32_e32 v80, v95, v80
	v_add_f32_e32 v80, v32, v80
	v_add_f32_e32 v80, v33, v80
	v_cvt_pk_bf16_f32 v122, v92, v93
	v_cvt_pk_bf16_f32 v123, v94, v95
	ds_read_b64_tr_b16 v[156:157], v168 offset:26624
	ds_read_b64_tr_b16 v[158:159], v168 offset:27136
	v_mfma_f32_32x32x16_bf16 v[64:79], v[140:143], v[100:103], v[64:79]
	v_add_f32_e32 v80, v34, v80
	v_add_f32_e32 v80, v35, v80
	v_add_f32_e32 v80, v36, v80
	v_add_f32_e32 v80, v37, v80
	v_cvt_pk_bf16_f32 v112, v32, v33
	v_cvt_pk_bf16_f32 v113, v34, v35
	ds_read_b64_tr_b16 v[144:145], v168 offset:30720
	ds_read_b64_tr_b16 v[146:147], v168 offset:31232
	v_mfma_f32_32x32x16_bf16 v[48:63], v[132:135], v[100:103], v[48:63]
	v_add_f32_e32 v32, v38, v80
	v_add_f32_e32 v32, v39, v32
	v_add_f32_e32 v32, v40, v32
	v_add_f32_e32 v32, v41, v32
	v_cvt_pk_bf16_f32 v114, v36, v37
	v_cvt_pk_bf16_f32 v115, v38, v39
	ds_read_b64_tr_b16 v[140:141], v168 offset:27648
	ds_read_b64_tr_b16 v[142:143], v168 offset:28160
	v_mfma_f32_32x32x16_bf16 v[64:79], v[136:139], v[96:99], v[64:79]
	v_add_f32_e32 v32, v42, v32
	v_add_f32_e32 v32, v43, v32
	v_add_f32_e32 v32, v44, v32
	v_add_f32_e32 v32, v45, v32
	v_cvt_pk_bf16_f32 v104, v40, v41
	v_cvt_pk_bf16_f32 v105, v42, v43
	ds_read_b64_tr_b16 v[132:133], v168 offset:31744
	ds_read_b64_tr_b16 v[134:135], v168 offset:32256
	v_mfma_f32_32x32x16_bf16 v[48:63], v[128:131], v[96:99], v[48:63]
	v_add_f32_e32 v32, v46, v32
	v_add_f32_e32 v34, v47, v32
	v_cvt_pk_bf16_f32 v106, v44, v45
	v_cvt_pk_bf16_f32 v107, v46, v47
	v_lshl_add_u64 v[32:33], v[178:179], 0, s[90:91]
	s_add_i32 s6, s41, s18
	s_mov_b32 m0, s6
	s_nop 0
	global_load_lds_dwordx4 v[32:33], off
	v_lshl_add_u64 v[32:33], v[176:177], 0, s[90:91]
	s_add_i32 s6, s28, s19
	s_mov_b32 m0, s6
	s_nop 0
	global_load_lds_dwordx4 v[32:33], off
	v_max_f32_e32 v32, v65, v65
	v_max_f32_e32 v33, v64, v64
	v_max_f32_e32 v32, v33, v32
	v_max3_f32 v33, v66, v67, v49
	v_max3_f32 v32, v32, v48, v50
	v_max3_f32 v32, v32, v51, v68
	v_max3_f32 v33, v33, v70, v71
	v_max3_f32 v32, v32, v69, v52
	v_max3_f32 v33, v33, v54, v55
	v_max3_f32 v32, v32, v53, v72
	v_max3_f32 v33, v33, v74, v75
	v_max3_f32 v32, v32, v73, v56
	v_max3_f32 v33, v33, v58, v59
	v_max3_f32 v32, v32, v57, v76
	v_max3_f32 v33, v33, v78, v79
	v_max3_f32 v32, v32, v77, v60
	v_max3_f32 v33, v33, v62, v63
	v_max3_f32 v32, v32, v61, v33
	v_mov_b32_e32 v33, v32
	s_nop 1
	v_permlane32_swap_b32_e32 v32, v33
	v_max_f32_e32 v32, v32, v33
	v_cmp_lt_f32_e32 vcc, s47, v32
	s_cmp_lg_u64 vcc, 0
	v_add_f32_e32 v181, v222, v34
	s_cselect_b64 s[6:7], -1, 0
	s_cbranch_vccnz .LBB0_156

.LBB0_151:
	s_add_i32 s6, s28, 0x2000
	s_cmpk_lg_i32 s28, 0x4000
	s_cselect_b32 s22, s6, 0
	v_add_u32_e32 v182, s41, v221
	ds_read_b64_tr_b16 v[144:145], v182 offset:24576
	ds_read_b64_tr_b16 v[146:147], v182 offset:25088
	v_mfma_f32_32x32x16_bf16 v[80:95], v[168:171], v[116:119], v[80:95]
	v_add_f32_e32 v104, v64, v65
	v_add_f32_e32 v104, v66, v104
	v_add_f32_e32 v104, v67, v104
	v_add_f32_e32 v104, v68, v104
	v_add_f32_e32 v104, v69, v104
	v_cvt_pk_bf16_f32 v124, v64, v65
	v_cvt_pk_bf16_f32 v125, v66, v67
	ds_read_b64_tr_b16 v[140:141], v182 offset:28672
	ds_read_b64_tr_b16 v[142:143], v182 offset:29184
	v_mfma_f32_32x32x16_bf16 v[32:47], v[128:131], v[116:119], v[32:47]
	v_add_f32_e32 v64, v70, v104
	v_add_f32_e32 v64, v71, v64
	v_add_f32_e32 v64, v72, v64
	v_add_f32_e32 v64, v73, v64
	v_cvt_pk_bf16_f32 v126, v68, v69
	v_cvt_pk_bf16_f32 v127, v70, v71
	ds_read_b64_tr_b16 v[132:133], v182 offset:25600
	ds_read_b64_tr_b16 v[134:135], v182 offset:26112
	v_mfma_f32_32x32x16_bf16 v[80:95], v[164:167], v[108:111], v[80:95]
	v_add_f32_e32 v64, v74, v64
	v_add_f32_e32 v64, v75, v64
	v_add_f32_e32 v64, v76, v64
	v_add_f32_e32 v64, v77, v64
	v_cvt_pk_bf16_f32 v120, v72, v73
	v_cvt_pk_bf16_f32 v121, v74, v75
	ds_read_b64_tr_b16 v[128:129], v182 offset:29696
	ds_read_b64_tr_b16 v[130:131], v182 offset:30208
	v_mfma_f32_32x32x16_bf16 v[32:47], v[152:155], v[108:111], v[32:47]
	v_add_f32_e32 v64, v78, v64
	v_add_f32_e32 v64, v79, v64
	v_add_f32_e32 v64, v48, v64
	v_add_f32_e32 v64, v49, v64
	v_cvt_pk_bf16_f32 v122, v76, v77
	v_cvt_pk_bf16_f32 v123, v78, v79
	ds_read_b64_tr_b16 v[172:173], v182 offset:26624
	ds_read_b64_tr_b16 v[174:175], v182 offset:27136
	v_mfma_f32_32x32x16_bf16 v[80:95], v[160:163], v[100:103], v[80:95]
	v_add_f32_e32 v64, v50, v64
	v_add_f32_e32 v64, v51, v64
	v_add_f32_e32 v64, v52, v64
	v_add_f32_e32 v64, v53, v64
	v_cvt_pk_bf16_f32 v112, v48, v49
	v_cvt_pk_bf16_f32 v113, v50, v51
	ds_read_b64_tr_b16 v[168:169], v182 offset:30720
	ds_read_b64_tr_b16 v[170:171], v182 offset:31232
	v_mfma_f32_32x32x16_bf16 v[32:47], v[148:151], v[100:103], v[32:47]
	v_add_f32_e32 v48, v54, v64
	v_add_f32_e32 v48, v55, v48
	v_add_f32_e32 v48, v56, v48
	v_add_f32_e32 v48, v57, v48
	v_cvt_pk_bf16_f32 v114, v52, v53
	v_cvt_pk_bf16_f32 v115, v54, v55
	ds_read_b64_tr_b16 v[164:165], v182 offset:27648
	ds_read_b64_tr_b16 v[166:167], v182 offset:28160
	v_mfma_f32_32x32x16_bf16 v[80:95], v[156:159], v[96:99], v[80:95]
	v_add_f32_e32 v48, v58, v48
	v_add_f32_e32 v48, v59, v48
	v_add_f32_e32 v48, v60, v48
	v_add_f32_e32 v48, v61, v48
	v_cvt_pk_bf16_f32 v104, v56, v57
	v_cvt_pk_bf16_f32 v105, v58, v59
	ds_read_b64_tr_b16 v[160:161], v182 offset:31744
	ds_read_b64_tr_b16 v[162:163], v182 offset:32256
	v_mfma_f32_32x32x16_bf16 v[32:47], v[136:139], v[96:99], v[32:47]
	v_add_f32_e32 v48, v62, v48
	v_add_f32_e32 v48, v63, v48
	v_cvt_pk_bf16_f32 v106, v60, v61
	v_cvt_pk_bf16_f32 v107, v62, v63
	v_max_f32_e32 v49, v81, v81
	v_max_f32_e32 v50, v80, v80
	v_max_f32_e32 v49, v50, v49
	s_nop 3
	v_max3_f32 v50, v82, v83, v33
	v_max3_f32 v49, v49, v32, v34
	v_max3_f32 v49, v49, v35, v84
	v_max3_f32 v50, v50, v86, v87
	v_max3_f32 v49, v49, v85, v36
	v_max3_f32 v50, v50, v38, v39
	v_max3_f32 v49, v49, v37, v88
	v_max3_f32 v50, v50, v90, v91
	v_max3_f32 v49, v49, v89, v40
	v_max3_f32 v50, v50, v42, v43
	v_max3_f32 v49, v49, v41, v92
	v_max3_f32 v50, v50, v94, v95
	v_max3_f32 v49, v49, v93, v44
	v_max3_f32 v50, v50, v46, v47
	v_add_f32_e32 v222, v181, v48
	v_max3_f32 v48, v49, v45, v50
	v_mov_b32_e32 v49, v48
	s_nop 1
	v_permlane32_swap_b32_e32 v48, v49
	s_add_i32 s6, s28, s18
	s_mov_b32 m0, s6
	s_nop 0
	global_load_lds_dwordx4 v[178:179], off
	v_max_f32_e32 v48, v48, v49
	s_add_i32 s6, s22, s19
	s_mov_b32 m0, s6
	s_nop 0
	global_load_lds_dwordx4 v[176:177], off
	v_cmp_lt_f32_e32 vcc, s47, v48
	s_cmp_lg_u64 vcc, 0
	s_cselect_b64 s[6:7], -1, 0
	s_cbranch_vccnz .LBB0_159

.LBB0_167:
	v_add_u32_e32 v164, s24, v221
	ds_read_b64_tr_b16 v[160:161], v164 offset:24576
	ds_read_b64_tr_b16 v[162:163], v164 offset:25088
	v_mfma_f32_32x32x16_bf16 v[64:79], v[156:159], v[116:119], v[64:79]
	v_add_f32_e32 v104, v80, v81
	v_add_f32_e32 v104, v82, v104
	v_add_f32_e32 v104, v83, v104
	v_add_f32_e32 v104, v84, v104
	v_add_f32_e32 v104, v85, v104
	v_cvt_pk_bf16_f32 v124, v80, v81
	v_cvt_pk_bf16_f32 v125, v82, v83
	ds_read_b64_tr_b16 v[156:157], v164 offset:28672
	ds_read_b64_tr_b16 v[158:159], v164 offset:29184
	v_mfma_f32_32x32x16_bf16 v[48:63], v[152:155], v[116:119], v[48:63]
	v_add_f32_e32 v104, v86, v104
	v_add_f32_e32 v104, v87, v104
	v_add_f32_e32 v104, v88, v104
	v_add_f32_e32 v104, v89, v104
	v_cvt_pk_bf16_f32 v126, v84, v85
	v_cvt_pk_bf16_f32 v127, v86, v87
	ds_read_b64_tr_b16 v[152:153], v164 offset:25600
	ds_read_b64_tr_b16 v[154:155], v164 offset:26112
	v_mfma_f32_32x32x16_bf16 v[64:79], v[148:151], v[108:111], v[64:79]
	v_add_f32_e32 v104, v90, v104
	v_add_f32_e32 v104, v91, v104
	v_add_f32_e32 v104, v92, v104
	v_add_f32_e32 v104, v93, v104
	v_cvt_pk_bf16_f32 v120, v88, v89
	v_cvt_pk_bf16_f32 v121, v90, v91
	ds_read_b64_tr_b16 v[148:149], v164 offset:29696
	ds_read_b64_tr_b16 v[150:151], v164 offset:30208
	v_mfma_f32_32x32x16_bf16 v[48:63], v[144:147], v[108:111], v[48:63]
	v_add_f32_e32 v104, v94, v104
	v_add_f32_e32 v104, v95, v104
	v_add_f32_e32 v104, v32, v104
	v_add_f32_e32 v104, v33, v104
	v_cvt_pk_bf16_f32 v122, v92, v93
	v_cvt_pk_bf16_f32 v123, v94, v95
	ds_read_b64_tr_b16 v[144:145], v164 offset:26624
	ds_read_b64_tr_b16 v[146:147], v164 offset:27136
	v_mfma_f32_32x32x16_bf16 v[64:79], v[140:143], v[100:103], v[64:79]
	v_add_f32_e32 v104, v34, v104
	v_add_f32_e32 v104, v35, v104
	v_add_f32_e32 v104, v36, v104
	v_add_f32_e32 v104, v37, v104
	v_cvt_pk_bf16_f32 v112, v32, v33
	v_cvt_pk_bf16_f32 v113, v34, v35
	ds_read_b64_tr_b16 v[116:117], v164 offset:30720
	ds_read_b64_tr_b16 v[118:119], v164 offset:31232
	v_mfma_f32_32x32x16_bf16 v[48:63], v[132:135], v[100:103], v[48:63]
	v_add_f32_e32 v100, v38, v104
	v_add_f32_e32 v100, v39, v100
	v_add_f32_e32 v100, v40, v100
	v_add_f32_e32 v100, v41, v100
	v_cvt_pk_bf16_f32 v114, v36, v37
	v_cvt_pk_bf16_f32 v115, v38, v39
	ds_read_b64_tr_b16 v[108:109], v164 offset:27648
	ds_read_b64_tr_b16 v[110:111], v164 offset:28160
	v_mfma_f32_32x32x16_bf16 v[64:79], v[136:139], v[96:99], v[64:79]
	v_add_f32_e32 v100, v42, v100
	v_add_f32_e32 v100, v43, v100
	v_add_f32_e32 v100, v44, v100
	v_add_f32_e32 v132, v45, v100
	v_cvt_pk_bf16_f32 v104, v40, v41
	v_cvt_pk_bf16_f32 v105, v42, v43
	ds_read_b64_tr_b16 v[100:101], v164 offset:31744
	ds_read_b64_tr_b16 v[102:103], v164 offset:32256
	v_mfma_f32_32x32x16_bf16 v[48:63], v[128:131], v[96:99], v[48:63]
	v_add_f32_e32 v96, v46, v132
	v_add_f32_e32 v96, v47, v96
	v_cvt_pk_bf16_f32 v106, v44, v45
	v_cvt_pk_bf16_f32 v107, v46, v47
	v_or_b32_e32 v98, 0xe0, v218
	v_or_b32_e32 v97, 0xc0, v218
	v_cmp_le_i32_e32 vcc, v98, v219
	v_add_f32_e32 v96, v222, v96
	s_nop 2
	v_cndmask_b32_e32 v48, v238, v48, vcc
	v_cmp_lt_i32_e32 vcc, v97, v219
	s_nop 1
	v_cndmask_b32_e32 v65, v238, v65, vcc
	v_cmp_le_i32_e32 vcc, v97, v219
	v_or_b32_e32 v97, 0xe1, v218
	s_nop 0
	v_cndmask_b32_e32 v64, v238, v64, vcc
	v_cmp_le_i32_e32 vcc, v97, v219
	v_or_b32_e32 v97, 0xc2, v218
	v_max_f32_e32 v98, v64, v64
	v_cndmask_b32_e32 v49, v238, v49, vcc
	v_cmp_le_i32_e32 vcc, v97, v219
	v_or_b32_e32 v97, 0xe2, v218
	s_nop 0
	v_cndmask_b32_e32 v66, v238, v66, vcc
	v_cmp_le_i32_e32 vcc, v97, v219
	v_or_b32_e32 v97, 0xc3, v218
	s_nop 0
	v_cndmask_b32_e32 v50, v238, v50, vcc
	v_cmp_le_i32_e32 vcc, v97, v219
	v_or_b32_e32 v97, 0xe3, v218
	s_nop 0
	v_cndmask_b32_e32 v67, v238, v67, vcc
	v_cmp_le_i32_e32 vcc, v97, v219
	v_or_b32_e32 v97, 0xc8, v218
	s_nop 0
	v_cndmask_b32_e32 v51, v238, v51, vcc
	v_cmp_le_i32_e32 vcc, v97, v219
	v_or_b32_e32 v97, 0xe8, v218
	s_nop 0
	v_cndmask_b32_e32 v68, v238, v68, vcc
	v_cmp_le_i32_e32 vcc, v97, v219
	v_or_b32_e32 v97, 0xc9, v218
	s_nop 0
	v_cndmask_b32_e32 v52, v238, v52, vcc
	v_cmp_le_i32_e32 vcc, v97, v219
	v_or_b32_e32 v97, 0xe9, v218
	s_nop 0
	v_cndmask_b32_e32 v69, v238, v69, vcc
	v_cmp_le_i32_e32 vcc, v97, v219
	v_or_b32_e32 v97, 0xca, v218
	s_nop 0
	v_cndmask_b32_e32 v53, v238, v53, vcc
	v_cmp_le_i32_e32 vcc, v97, v219
	v_or_b32_e32 v97, 0xea, v218
	s_nop 0
	v_cndmask_b32_e32 v70, v238, v70, vcc
	v_cmp_le_i32_e32 vcc, v97, v219
	v_or_b32_e32 v97, 0xcb, v218
	s_nop 0
	v_cndmask_b32_e32 v54, v238, v54, vcc
	v_cmp_le_i32_e32 vcc, v97, v219
	v_or_b32_e32 v97, 0xeb, v218
	s_nop 0
	v_cndmask_b32_e32 v71, v238, v71, vcc
	v_cmp_le_i32_e32 vcc, v97, v219
	v_or_b32_e32 v97, 0xd0, v218
	s_nop 0
	v_cndmask_b32_e32 v55, v238, v55, vcc
	v_cmp_le_i32_e32 vcc, v97, v219
	v_or_b32_e32 v97, 0xf0, v218
	s_nop 0
	v_cndmask_b32_e32 v72, v238, v72, vcc
	v_cmp_le_i32_e32 vcc, v97, v219
	v_or_b32_e32 v97, 0xd1, v218
	s_nop 0
	v_cndmask_b32_e32 v56, v238, v56, vcc
	v_cmp_le_i32_e32 vcc, v97, v219
	v_or_b32_e32 v97, 0xf1, v218
	s_nop 0
	v_cndmask_b32_e32 v73, v238, v73, vcc
	v_cmp_le_i32_e32 vcc, v97, v219
	v_or_b32_e32 v97, 0xd2, v218
	s_nop 0
	v_cndmask_b32_e32 v57, v238, v57, vcc
	v_cmp_le_i32_e32 vcc, v97, v219
	v_or_b32_e32 v97, 0xf2, v218
	s_nop 0
	v_cndmask_b32_e32 v74, v238, v74, vcc
	v_cmp_le_i32_e32 vcc, v97, v219
	v_or_b32_e32 v97, 0xd3, v218
	s_nop 0
	v_cndmask_b32_e32 v58, v238, v58, vcc
	v_cmp_le_i32_e32 vcc, v97, v219
	v_or_b32_e32 v97, 0xf3, v218
	s_nop 0
	v_cndmask_b32_e32 v75, v238, v75, vcc
	v_cmp_le_i32_e32 vcc, v97, v219
	v_or_b32_e32 v97, 0xd8, v218
	s_nop 0
	v_cndmask_b32_e32 v59, v238, v59, vcc
	v_cmp_le_i32_e32 vcc, v97, v219
	v_or_b32_e32 v97, 0xf8, v218
	s_nop 0
	v_cndmask_b32_e32 v76, v238, v76, vcc
	v_cmp_le_i32_e32 vcc, v97, v219
	v_or_b32_e32 v97, 0xd9, v218
	s_nop 0
	v_cndmask_b32_e32 v60, v238, v60, vcc
	v_cmp_le_i32_e32 vcc, v97, v219
	v_or_b32_e32 v97, 0xf9, v218
	s_nop 0
	v_cndmask_b32_e32 v77, v238, v77, vcc
	v_cmp_le_i32_e32 vcc, v97, v219
	v_or_b32_e32 v97, 0xda, v218
	s_nop 0
	v_cndmask_b32_e32 v61, v238, v61, vcc
	v_cmp_le_i32_e32 vcc, v97, v219
	v_or_b32_e32 v97, 0xfa, v218
	s_nop 0
	v_cndmask_b32_e32 v78, v238, v78, vcc
	v_cmp_le_i32_e32 vcc, v97, v219
	v_or_b32_e32 v97, 0xdb, v218
	s_nop 0
	v_cndmask_b32_e32 v62, v238, v62, vcc
	v_cmp_le_i32_e32 vcc, v97, v219
	v_or_b32_e32 v97, 0xfb, v218
	s_nop 0
	v_cndmask_b32_e32 v79, v238, v79, vcc
	v_cmp_le_i32_e32 vcc, v97, v219
	v_max_f32_e32 v97, v65, v65
	v_max_f32_e32 v97, v98, v97
	v_max3_f32 v98, v66, v67, v49
	v_max3_f32 v97, v97, v48, v50
	v_max3_f32 v97, v97, v51, v68
	v_max3_f32 v98, v98, v70, v71
	v_max3_f32 v97, v97, v69, v52
	v_max3_f32 v98, v98, v54, v55
	v_max3_f32 v97, v97, v53, v72
	v_max3_f32 v98, v98, v74, v75
	v_max3_f32 v97, v97, v73, v56
	v_max3_f32 v98, v98, v58, v59
	v_cndmask_b32_e32 v63, v238, v63, vcc
	v_max3_f32 v97, v97, v57, v76
	v_max3_f32 v98, v98, v78, v79
	v_max3_f32 v97, v97, v77, v60
	v_max3_f32 v98, v98, v62, v63
	v_max3_f32 v97, v97, v61, v98
	v_mov_b32_e32 v98, v97
	s_nop 1
	v_permlane32_swap_b32_e32 v97, v98
	v_max_f32_e32 v97, v97, v98
	v_cmp_lt_f32_e32 vcc, s47, v97
	s_cmp_lg_u64 vcc, 0
	s_cselect_b64 s[4:5], -1, 0
	s_cbranch_vccnz .LBB0_224

.LBB0_174:
	v_add_u32_e32 v162, s28, v221
	ds_read_b64_tr_b16 v[184:185], v162 offset:24576
	ds_read_b64_tr_b16 v[186:187], v162 offset:25088
	v_mfma_f32_32x32x16_bf16 v[64:79], v[156:159], v[116:119], v[64:79]
	v_add_f32_e32 v104, v80, v81
	v_add_f32_e32 v104, v82, v104
	v_add_f32_e32 v104, v83, v104
	v_add_f32_e32 v104, v84, v104
	v_add_f32_e32 v104, v85, v104
	v_cvt_pk_bf16_f32 v124, v80, v81
	v_cvt_pk_bf16_f32 v125, v82, v83
	ds_read_b64_tr_b16 v[156:157], v162 offset:28672
	ds_read_b64_tr_b16 v[158:159], v162 offset:29184
	v_mfma_f32_32x32x16_bf16 v[48:63], v[152:155], v[116:119], v[48:63]
	v_add_f32_e32 v80, v86, v104
	v_add_f32_e32 v80, v87, v80
	v_add_f32_e32 v80, v88, v80
	v_add_f32_e32 v80, v89, v80
	v_cvt_pk_bf16_f32 v126, v84, v85
	v_cvt_pk_bf16_f32 v127, v86, v87
	ds_read_b64_tr_b16 v[176:177], v162 offset:25600
	ds_read_b64_tr_b16 v[178:179], v162 offset:26112
	v_mfma_f32_32x32x16_bf16 v[64:79], v[148:151], v[108:111], v[64:79]
	v_add_f32_e32 v80, v90, v80
	v_add_f32_e32 v80, v91, v80
	v_add_f32_e32 v80, v92, v80
	v_add_f32_e32 v80, v93, v80
	v_cvt_pk_bf16_f32 v120, v88, v89
	v_cvt_pk_bf16_f32 v121, v90, v91
	ds_read_b64_tr_b16 v[172:173], v162 offset:29696
	ds_read_b64_tr_b16 v[174:175], v162 offset:30208
	v_mfma_f32_32x32x16_bf16 v[48:63], v[144:147], v[108:111], v[48:63]
	v_add_f32_e32 v80, v94, v80
	v_add_f32_e32 v80, v95, v80
	v_add_f32_e32 v80, v32, v80
	v_add_f32_e32 v80, v33, v80
	v_cvt_pk_bf16_f32 v122, v92, v93
	v_cvt_pk_bf16_f32 v123, v94, v95
	ds_read_b64_tr_b16 v[180:181], v162 offset:26624
	ds_read_b64_tr_b16 v[182:183], v162 offset:27136
	v_mfma_f32_32x32x16_bf16 v[64:79], v[140:143], v[100:103], v[64:79]
	v_add_f32_e32 v80, v34, v80
	v_add_f32_e32 v80, v35, v80
	v_add_f32_e32 v80, v36, v80
	v_add_f32_e32 v80, v37, v80
	v_cvt_pk_bf16_f32 v112, v32, v33
	v_cvt_pk_bf16_f32 v113, v34, v35
	ds_read_b64_tr_b16 v[168:169], v162 offset:30720
	ds_read_b64_tr_b16 v[170:171], v162 offset:31232
	v_mfma_f32_32x32x16_bf16 v[48:63], v[132:135], v[100:103], v[48:63]
	v_add_f32_e32 v32, v38, v80
	v_add_f32_e32 v32, v39, v32
	v_add_f32_e32 v32, v40, v32
	v_add_f32_e32 v32, v41, v32
	v_cvt_pk_bf16_f32 v114, v36, v37
	v_cvt_pk_bf16_f32 v115, v38, v39
	ds_read_b64_tr_b16 v[164:165], v162 offset:27648
	ds_read_b64_tr_b16 v[166:167], v162 offset:28160
	v_mfma_f32_32x32x16_bf16 v[64:79], v[136:139], v[96:99], v[64:79]
	v_add_f32_e32 v32, v42, v32
	v_add_f32_e32 v32, v43, v32
	v_add_f32_e32 v32, v44, v32
	v_add_f32_e32 v32, v45, v32
	v_cvt_pk_bf16_f32 v104, v40, v41
	v_cvt_pk_bf16_f32 v105, v42, v43
	ds_read_b64_tr_b16 v[160:161], v162 offset:31744
	ds_read_b64_tr_b16 v[162:163], v162 offset:32256
	v_mfma_f32_32x32x16_bf16 v[48:63], v[128:131], v[96:99], v[48:63]
	v_add_f32_e32 v32, v46, v32
	v_add_f32_e32 v32, v47, v32
	v_cvt_pk_bf16_f32 v106, v44, v45
	v_cvt_pk_bf16_f32 v107, v46, v47
	s_add_i32 s78, s4, 1
	s_cmp_ge_i32 s78, s20
	s_cselect_b64 s[40:41], -1, 0
	s_and_b64 vcc, exec, s[40:41]
	s_cbranch_vccnz .LBB0_176
	s_lshl_b64 s[16:17], s[78:79], 17
	s_add_i32 s5, s22, s18
	v_lshl_add_u64 v[34:35], v[206:207], 0, s[16:17]
	s_mov_b32 m0, s5
	s_nop 0
	global_load_lds_dwordx4 v[34:35], off

.LBB0_178:
	v_add_f32_e32 v205, v222, v32
	v_max_f32_e32 v32, v65, v65
	v_max_f32_e32 v33, v64, v64
	v_max_f32_e32 v32, v33, v32
	v_max3_f32 v33, v66, v67, v49
	v_max3_f32 v32, v32, v48, v50
	v_max3_f32 v32, v32, v51, v68
	v_max3_f32 v33, v33, v70, v71
	v_max3_f32 v32, v32, v69, v52
	v_max3_f32 v33, v33, v54, v55
	v_max3_f32 v32, v32, v53, v72
	v_max3_f32 v33, v33, v74, v75
	v_max3_f32 v32, v32, v73, v56
	v_max3_f32 v33, v33, v58, v59
	v_max3_f32 v32, v32, v57, v76
	v_max3_f32 v33, v33, v78, v79
	v_max3_f32 v32, v32, v77, v60
	v_max3_f32 v33, v33, v62, v63
	v_max3_f32 v32, v32, v61, v33
	v_mov_b32_e32 v33, v32
	s_nop 1
	v_permlane32_swap_b32_e32 v32, v33
	v_max_f32_e32 v32, v32, v33
	v_cmp_lt_f32_e32 vcc, s47, v32
	s_cmp_lg_u64 vcc, 0
	s_cselect_b64 s[52:53], -1, 0
	s_cbranch_vccnz .LBB0_218

.LBB0_183:
	v_add_u32_e32 v162, s22, v221
	ds_read_b64_tr_b16 v[188:189], v162 offset:24576
	ds_read_b64_tr_b16 v[190:191], v162 offset:25088
	v_mfma_f32_32x32x16_bf16 v[80:95], v[156:159], v[116:119], v[80:95]
	v_add_f32_e32 v104, v64, v65
	v_add_f32_e32 v104, v66, v104
	v_add_f32_e32 v104, v67, v104
	v_add_f32_e32 v104, v68, v104
	v_add_f32_e32 v104, v69, v104
	v_cvt_pk_bf16_f32 v124, v64, v65
	v_cvt_pk_bf16_f32 v125, v66, v67
	ds_read_b64_tr_b16 v[184:185], v162 offset:28672
	ds_read_b64_tr_b16 v[186:187], v162 offset:29184
	v_mfma_f32_32x32x16_bf16 v[32:47], v[152:155], v[116:119], v[32:47]
	v_add_f32_e32 v104, v70, v104
	v_add_f32_e32 v104, v71, v104
	v_add_f32_e32 v104, v72, v104
	v_add_f32_e32 v104, v73, v104
	v_cvt_pk_bf16_f32 v126, v68, v69
	v_cvt_pk_bf16_f32 v127, v70, v71
	ds_read_b64_tr_b16 v[180:181], v162 offset:25600
	ds_read_b64_tr_b16 v[182:183], v162 offset:26112
	v_mfma_f32_32x32x16_bf16 v[80:95], v[148:151], v[108:111], v[80:95]
	v_add_f32_e32 v104, v74, v104
	v_add_f32_e32 v104, v75, v104
	v_add_f32_e32 v104, v76, v104
	v_add_f32_e32 v104, v77, v104
	v_cvt_pk_bf16_f32 v120, v72, v73
	v_cvt_pk_bf16_f32 v121, v74, v75
	ds_read_b64_tr_b16 v[176:177], v162 offset:29696
	ds_read_b64_tr_b16 v[178:179], v162 offset:30208
	v_mfma_f32_32x32x16_bf16 v[32:47], v[144:147], v[108:111], v[32:47]
	v_add_f32_e32 v104, v78, v104
	v_add_f32_e32 v104, v79, v104
	v_add_f32_e32 v104, v48, v104
	v_add_f32_e32 v104, v49, v104
	v_cvt_pk_bf16_f32 v122, v76, v77
	v_cvt_pk_bf16_f32 v123, v78, v79
	ds_read_b64_tr_b16 v[172:173], v162 offset:26624
	ds_read_b64_tr_b16 v[174:175], v162 offset:27136
	v_mfma_f32_32x32x16_bf16 v[80:95], v[140:143], v[100:103], v[80:95]
	v_add_f32_e32 v104, v50, v104
	v_add_f32_e32 v104, v51, v104
	v_add_f32_e32 v104, v52, v104
	v_add_f32_e32 v104, v53, v104
	v_cvt_pk_bf16_f32 v112, v48, v49
	v_cvt_pk_bf16_f32 v113, v50, v51
	ds_read_b64_tr_b16 v[168:169], v162 offset:30720
	ds_read_b64_tr_b16 v[170:171], v162 offset:31232
	v_mfma_f32_32x32x16_bf16 v[32:47], v[132:135], v[100:103], v[32:47]
	v_add_f32_e32 v104, v54, v104
	v_add_f32_e32 v104, v55, v104
	v_add_f32_e32 v104, v56, v104
	v_add_f32_e32 v104, v57, v104
	v_cvt_pk_bf16_f32 v114, v52, v53
	v_cvt_pk_bf16_f32 v115, v54, v55
	ds_read_b64_tr_b16 v[164:165], v162 offset:27648
	ds_read_b64_tr_b16 v[166:167], v162 offset:28160
	v_mfma_f32_32x32x16_bf16 v[80:95], v[136:139], v[96:99], v[80:95]
	v_add_f32_e32 v104, v58, v104
	v_add_f32_e32 v104, v59, v104
	v_add_f32_e32 v104, v60, v104
	v_add_f32_e32 v222, v61, v104
	v_cvt_pk_bf16_f32 v104, v56, v57
	v_cvt_pk_bf16_f32 v105, v58, v59
	ds_read_b64_tr_b16 v[160:161], v162 offset:31744
	ds_read_b64_tr_b16 v[162:163], v162 offset:32256
	v_mfma_f32_32x32x16_bf16 v[32:47], v[128:131], v[96:99], v[32:47]
	v_add_f32_e32 v106, v62, v222
	v_add_f32_e32 v222, v63, v106
	v_cvt_pk_bf16_f32 v106, v60, v61
	v_cvt_pk_bf16_f32 v107, v62, v63
	s_add_i32 s78, s4, 2
	s_cmp_ge_i32 s78, s20
	s_cselect_b64 s[52:53], -1, 0
	s_and_b64 vcc, exec, s[52:53]
	s_cbranch_vccnz .LBB0_185
	s_lshl_b64 s[16:17], s[78:79], 17
	s_add_i32 s5, s24, s18
	v_lshl_add_u64 v[246:247], v[206:207], 0, s[16:17]
	s_mov_b32 m0, s5
	s_nop 0
	global_load_lds_dwordx4 v[246:247], off

.LBB0_189:
	v_add_f32_e32 v222, v205, v222
	v_max_f32_e32 v205, v81, v81
	v_max_f32_e32 v230, v80, v80
	v_max_f32_e32 v205, v230, v205
	v_max3_f32 v230, v82, v83, v33
	v_max3_f32 v205, v205, v32, v34
	v_max3_f32 v205, v205, v35, v84
	v_max3_f32 v230, v230, v86, v87
	v_max3_f32 v205, v205, v85, v36
	v_max3_f32 v230, v230, v38, v39
	v_max3_f32 v205, v205, v37, v88
	v_max3_f32 v230, v230, v90, v91
	v_max3_f32 v205, v205, v89, v40
	v_max3_f32 v230, v230, v42, v43
	v_max3_f32 v205, v205, v41, v92
	v_max3_f32 v230, v230, v94, v95
	v_max3_f32 v205, v205, v93, v44
	v_max3_f32 v230, v230, v46, v47
	v_max3_f32 v205, v205, v45, v230
	v_mov_b32_e32 v230, v205
	s_nop 1
	v_permlane32_swap_b32_e32 v205, v230
	v_max_f32_e32 v205, v205, v230
	v_cmp_lt_f32_e32 vcc, s47, v205
	s_cmp_lg_u64 vcc, 0
	s_cselect_b64 s[70:71], -1, 0
	s_cbranch_vccnz .LBB0_221
	v_cndmask_b32_e64 v205, 0, 1, s[16:17]
	v_cmp_ne_u32_e64 s[4:5], 1, v205
	s_andn2_b64 vcc, exec, s[16:17]
	s_cbranch_vccnz .LBB0_192
